# m1 + out-proj LN residual-row loads as an 11-deep rolling window (was 4 loads per full drain), row address pairs preserved
# speedup vs baseline: 1.0017x; 1.0017x over previous
.LBB0_3244:
	s_lshl_b32 s0, s18, 5
	s_lshl_b32 s1, s42, 8
	s_or_b32 s0, s1, s0
	v_lshrrev_b32_e32 v130, 2, v167
	v_and_or_b32 v162, v130, 12, s0
	s_ashr_i32 s0, s16, 31
	s_lshr_b32 s0, s0, 28
	s_add_i32 s0, s16, s0
	s_ashr_i32 s0, s0, 4
	s_mul_hi_i32 s1, s0, 0x2400
	s_mulk_i32 s0, 0x2400
	s_lshl_b32 s19, s16, 8
	s_lshl_b64 s[52:53], s[0:1], 2
	s_add_u32 s0, s6, s52
	v_ashrrev_i32_e32 v163, 31, v162
	s_addc_u32 s1, s7, s53
	v_lshlrev_b64 v[164:165], 2, v[162:163]
	v_lshl_add_u64 v[130:131], s[0:1], 0, v[164:165]
	s_add_i32 s0, s19, s20
	v_or_b32_e32 v160, s0, v168
	v_ashrrev_i32_e32 v161, 31, v160
	v_lshlrev_b64 v[132:133], 12, v[160:161]
	v_lshl_add_u64 v[132:133], s[44:45], 0, v[132:133]
	s_mov_b32 s0, 0x105000
	v_lshl_add_u64 v[146:147], v[132:133], 0, v[164:165]
	v_add_co_u32_e32 v132, vcc, s0, v130
	s_mov_b64 s[0:1], 0x105000
	s_nop 0
	v_addc_co_u32_e32 v133, vcc, 0, v131, vcc
	v_lshl_add_u64 v[130:131], v[130:131], 0, s[0:1]
	global_load_dwordx4 v[134:137], v[132:133], off
	global_load_dwordx4 v[142:145], v[130:131], off offset:64
	global_load_dwordx4 v[138:141], v[130:131], off offset:512
	s_nop 0
	global_load_dwordx4 v[130:133], v[130:131], off offset:576
	s_mov_b32 s0, 0x3f9837f0
	v_and_b32_e32 v169, 64, v220
	v_xor_b32_e32 v161, 16, v220
	v_add_u32_e32 v188, 64, v169
	v_cmp_lt_i32_e32 vcc, v161, v188
	global_load_dwordx4 v[170:173], v[146:147], off
	global_load_dwordx4 v[174:177], v[146:147], off offset:64
	global_load_dwordx4 v[178:181], v[146:147], off offset:512
	global_load_dwordx4 v[182:185], v[146:147], off offset:576
	v_or_b32_e32 v148, 16, v160
	v_ashrrev_i32_e32 v149, 31, v148
	v_lshlrev_b64 v[148:149], 12, v[148:149]
	v_lshl_add_u64 v[148:149], s[44:45], 0, v[148:149]
	v_lshl_add_u64 v[148:149], v[148:149], 0, v[164:165]
	global_load_dwordx4 v[226:229], v[148:149], off
	global_load_dwordx4 v[230:233], v[148:149], off offset:64
	global_load_dwordx4 v[234:237], v[148:149], off offset:512
	global_load_dwordx4 v[238:241], v[148:149], off offset:576
	v_or_b32_e32 v150, 32, v160
	v_ashrrev_i32_e32 v151, 31, v150
	v_lshlrev_b64 v[150:151], 12, v[150:151]
	v_lshl_add_u64 v[150:151], s[44:45], 0, v[150:151]
	v_lshl_add_u64 v[150:151], v[150:151], 0, v[164:165]
	global_load_dwordx4 v[242:245], v[150:151], off
	global_load_dwordx4 v[200:203], v[150:151], off offset:64
	global_load_dwordx4 v[204:207], v[150:151], off offset:512
	s_waitcnt vmcnt(10)
	v_pk_mul_f32 v[172:173], v[172:173], s[0:1] op_sel_hi:[1,0]
	v_pk_mul_f32 v[170:171], v[170:171], s[0:1] op_sel_hi:[1,0]
	v_pk_fma_f32 v[128:129], v[128:129], v[136:137], v[172:173]
	v_pk_fma_f32 v[126:127], v[126:127], v[134:135], v[170:171]
	global_load_dwordx4 v[170:173], v[150:151], off offset:576
	s_waitcnt vmcnt(10)
	v_pk_mul_f32 v[176:177], v[176:177], s[0:1] op_sel_hi:[1,0]
	v_pk_mul_f32 v[174:175], v[174:175], s[0:1] op_sel_hi:[1,0]
	v_pk_fma_f32 v[68:69], v[68:69], v[144:145], v[176:177]
	v_pk_fma_f32 v[66:67], v[66:67], v[142:143], v[174:175]
	v_or_b32_e32 v152, 48, v160
	v_ashrrev_i32_e32 v153, 31, v152
	v_lshlrev_b64 v[152:153], 12, v[152:153]
	v_lshl_add_u64 v[152:153], s[44:45], 0, v[152:153]
	v_lshl_add_u64 v[152:153], v[152:153], 0, v[164:165]
	global_load_dwordx4 v[174:177], v[152:153], off
	s_waitcnt vmcnt(10)
	v_pk_mul_f32 v[180:181], v[180:181], s[0:1] op_sel_hi:[1,0]
	v_pk_mul_f32 v[178:179], v[178:179], s[0:1] op_sel_hi:[1,0]
	v_pk_fma_f32 v[36:37], v[36:37], v[140:141], v[180:181]
	v_pk_fma_f32 v[34:35], v[34:35], v[138:139], v[178:179]
	global_load_dwordx4 v[178:181], v[152:153], off offset:64
	s_waitcnt vmcnt(10)
	v_pk_mul_f32 v[184:185], v[184:185], s[0:1] op_sel_hi:[1,0]
	v_pk_mul_f32 v[182:183], v[182:183], s[0:1] op_sel_hi:[1,0]
	v_pk_fma_f32 v[4:5], v[4:5], v[132:133], v[184:185]
	v_pk_fma_f32 v[2:3], v[2:3], v[130:131], v[182:183]
	global_load_dwordx4 v[182:185], v[152:153], off offset:512
	v_cndmask_b32_e32 v161, v220, v161, vcc
	v_lshlrev_b32_e32 v169, 2, v161
	v_mov_b32_e32 v208, v127
	v_mov_b32_e32 v209, v128
	v_mov_b32_e32 v210, v126
	v_mov_b32_e32 v211, v129
	v_mov_b32_e32 v212, v67
	v_mov_b32_e32 v213, v68
	v_pk_add_f32 v[208:209], v[208:209], v[210:211]
	s_waitcnt vmcnt(10)
	v_pk_mul_f32 v[228:229], v[228:229], s[0:1] op_sel_hi:[1,0]
	v_pk_mul_f32 v[226:227], v[226:227], s[0:1] op_sel_hi:[1,0]
	v_pk_fma_f32 v[124:125], v[124:125], v[136:137], v[228:229]
	v_pk_fma_f32 v[122:123], v[122:123], v[134:135], v[226:227]
	global_load_dwordx4 v[226:229], v[152:153], off offset:576
	s_waitcnt vmcnt(10)
	v_pk_mul_f32 v[232:233], v[232:233], s[0:1] op_sel_hi:[1,0]
	v_pk_mul_f32 v[230:231], v[230:231], s[0:1] op_sel_hi:[1,0]
	v_pk_fma_f32 v[72:73], v[72:73], v[144:145], v[232:233]
	v_pk_fma_f32 v[70:71], v[70:71], v[142:143], v[230:231]
	v_add_u32_e32 v154, 0x80, v160
	v_ashrrev_i32_e32 v155, 31, v154
	v_lshlrev_b64 v[154:155], 12, v[154:155]
	v_lshl_add_u64 v[154:155], s[44:45], 0, v[154:155]
	v_lshl_add_u64 v[154:155], v[154:155], 0, v[164:165]
	global_load_dwordx4 v[230:233], v[154:155], off
	s_waitcnt vmcnt(10)
	v_pk_mul_f32 v[236:237], v[236:237], s[0:1] op_sel_hi:[1,0]
	v_pk_mul_f32 v[234:235], v[234:235], s[0:1] op_sel_hi:[1,0]
	v_pk_fma_f32 v[40:41], v[40:41], v[140:141], v[236:237]
	v_pk_fma_f32 v[38:39], v[38:39], v[138:139], v[234:235]
	global_load_dwordx4 v[234:237], v[154:155], off offset:64
	s_waitcnt vmcnt(10)
	v_pk_mul_f32 v[240:241], v[240:241], s[0:1] op_sel_hi:[1,0]
	v_pk_mul_f32 v[238:239], v[238:239], s[0:1] op_sel_hi:[1,0]
	v_pk_fma_f32 v[8:9], v[8:9], v[132:133], v[240:241]
	v_pk_fma_f32 v[6:7], v[6:7], v[130:131], v[238:239]
	global_load_dwordx4 v[238:241], v[154:155], off offset:512
	s_waitcnt vmcnt(10)
	v_pk_mul_f32 v[244:245], v[244:245], s[0:1] op_sel_hi:[1,0]
	v_pk_mul_f32 v[242:243], v[242:243], s[0:1] op_sel_hi:[1,0]
	v_pk_fma_f32 v[120:121], v[120:121], v[136:137], v[244:245]
	v_pk_fma_f32 v[118:119], v[118:119], v[134:135], v[242:243]
	global_load_dwordx4 v[242:245], v[154:155], off offset:576
	s_waitcnt vmcnt(10)
	v_pk_mul_f32 v[202:203], v[202:203], s[0:1] op_sel_hi:[1,0]
	v_pk_mul_f32 v[200:201], v[200:201], s[0:1] op_sel_hi:[1,0]
	v_pk_fma_f32 v[76:77], v[76:77], v[144:145], v[202:203]
	v_pk_fma_f32 v[74:75], v[74:75], v[142:143], v[200:201]
	v_add_u32_e32 v156, 0x90, v160
	v_ashrrev_i32_e32 v157, 31, v156
	v_lshlrev_b64 v[156:157], 12, v[156:157]
	v_lshl_add_u64 v[156:157], s[44:45], 0, v[156:157]
	v_lshl_add_u64 v[156:157], v[156:157], 0, v[164:165]
	global_load_dwordx4 v[200:203], v[156:157], off
	s_waitcnt vmcnt(10)
	v_pk_mul_f32 v[206:207], v[206:207], s[0:1] op_sel_hi:[1,0]
	v_pk_mul_f32 v[204:205], v[204:205], s[0:1] op_sel_hi:[1,0]
	v_pk_fma_f32 v[44:45], v[44:45], v[140:141], v[206:207]
	v_pk_fma_f32 v[42:43], v[42:43], v[138:139], v[204:205]
	global_load_dwordx4 v[204:207], v[156:157], off offset:64
	s_waitcnt vmcnt(10)
	v_pk_mul_f32 v[172:173], v[172:173], s[0:1] op_sel_hi:[1,0]
	v_pk_mul_f32 v[170:171], v[170:171], s[0:1] op_sel_hi:[1,0]
	v_pk_fma_f32 v[12:13], v[12:13], v[132:133], v[172:173]
	v_pk_fma_f32 v[10:11], v[10:11], v[130:131], v[170:171]
	global_load_dwordx4 v[170:173], v[156:157], off offset:512
	s_waitcnt vmcnt(10)
	v_pk_mul_f32 v[176:177], v[176:177], s[0:1] op_sel_hi:[1,0]
	v_pk_mul_f32 v[174:175], v[174:175], s[0:1] op_sel_hi:[1,0]
	v_pk_fma_f32 v[116:117], v[116:117], v[136:137], v[176:177]
	v_pk_fma_f32 v[114:115], v[114:115], v[134:135], v[174:175]
	global_load_dwordx4 v[174:177], v[156:157], off offset:576
	s_waitcnt vmcnt(10)
	v_pk_mul_f32 v[180:181], v[180:181], s[0:1] op_sel_hi:[1,0]
	v_pk_mul_f32 v[178:179], v[178:179], s[0:1] op_sel_hi:[1,0]
	v_pk_fma_f32 v[80:81], v[80:81], v[144:145], v[180:181]
	v_pk_fma_f32 v[78:79], v[78:79], v[142:143], v[178:179]
	v_add_u32_e32 v158, 0xa0, v160
	v_ashrrev_i32_e32 v159, 31, v158
	v_lshlrev_b64 v[158:159], 12, v[158:159]
	v_lshl_add_u64 v[158:159], s[44:45], 0, v[158:159]
	v_lshl_add_u64 v[158:159], v[158:159], 0, v[164:165]
	global_load_dwordx4 v[178:181], v[158:159], off
	s_waitcnt vmcnt(10)
	v_pk_mul_f32 v[184:185], v[184:185], s[0:1] op_sel_hi:[1,0]
	v_pk_mul_f32 v[182:183], v[182:183], s[0:1] op_sel_hi:[1,0]
	v_pk_fma_f32 v[48:49], v[48:49], v[140:141], v[184:185]
	v_pk_fma_f32 v[46:47], v[46:47], v[138:139], v[182:183]
	global_load_dwordx4 v[182:185], v[158:159], off offset:64
	s_waitcnt vmcnt(10)
	v_pk_mul_f32 v[228:229], v[228:229], s[0:1] op_sel_hi:[1,0]
	v_pk_mul_f32 v[226:227], v[226:227], s[0:1] op_sel_hi:[1,0]
	v_pk_fma_f32 v[16:17], v[16:17], v[132:133], v[228:229]
	v_pk_fma_f32 v[14:15], v[14:15], v[130:131], v[226:227]
	global_load_dwordx4 v[226:229], v[158:159], off offset:512
	s_waitcnt vmcnt(10)
	v_pk_mul_f32 v[232:233], v[232:233], s[0:1] op_sel_hi:[1,0]
	v_pk_mul_f32 v[230:231], v[230:231], s[0:1] op_sel_hi:[1,0]
	v_pk_fma_f32 v[108:109], v[108:109], v[136:137], v[232:233]
	v_pk_fma_f32 v[106:107], v[106:107], v[134:135], v[230:231]
	global_load_dwordx4 v[230:233], v[158:159], off offset:576
	s_waitcnt vmcnt(10)
	v_pk_mul_f32 v[236:237], v[236:237], s[0:1] op_sel_hi:[1,0]
	v_pk_mul_f32 v[234:235], v[234:235], s[0:1] op_sel_hi:[1,0]
	v_pk_fma_f32 v[84:85], v[84:85], v[144:145], v[236:237]
	v_pk_fma_f32 v[82:83], v[82:83], v[142:143], v[234:235]
	s_waitcnt vmcnt(9)
	v_pk_mul_f32 v[240:241], v[240:241], s[0:1] op_sel_hi:[1,0]
	v_pk_mul_f32 v[238:239], v[238:239], s[0:1] op_sel_hi:[1,0]
	v_pk_fma_f32 v[52:53], v[52:53], v[140:141], v[240:241]
	v_pk_fma_f32 v[50:51], v[50:51], v[138:139], v[238:239]
	s_waitcnt vmcnt(8)
	v_pk_mul_f32 v[244:245], v[244:245], s[0:1] op_sel_hi:[1,0]
	v_pk_mul_f32 v[242:243], v[242:243], s[0:1] op_sel_hi:[1,0]
	v_pk_fma_f32 v[20:21], v[20:21], v[132:133], v[244:245]
	v_pk_fma_f32 v[18:19], v[18:19], v[130:131], v[242:243]
	s_waitcnt vmcnt(7)
	v_pk_mul_f32 v[202:203], v[202:203], s[0:1] op_sel_hi:[1,0]
	v_pk_mul_f32 v[200:201], v[200:201], s[0:1] op_sel_hi:[1,0]
	v_pk_fma_f32 v[112:113], v[112:113], v[136:137], v[202:203]
	v_pk_fma_f32 v[110:111], v[110:111], v[134:135], v[200:201]
	s_waitcnt vmcnt(6)
	v_pk_mul_f32 v[206:207], v[206:207], s[0:1] op_sel_hi:[1,0]
	v_pk_mul_f32 v[204:205], v[204:205], s[0:1] op_sel_hi:[1,0]
	v_pk_fma_f32 v[88:89], v[88:89], v[144:145], v[206:207]
	v_pk_fma_f32 v[86:87], v[86:87], v[142:143], v[204:205]
	s_waitcnt vmcnt(5)
	v_pk_mul_f32 v[172:173], v[172:173], s[0:1] op_sel_hi:[1,0]
	v_pk_mul_f32 v[170:171], v[170:171], s[0:1] op_sel_hi:[1,0]
	v_pk_fma_f32 v[56:57], v[56:57], v[140:141], v[172:173]
	v_pk_fma_f32 v[54:55], v[54:55], v[138:139], v[170:171]
	s_waitcnt vmcnt(4)
	v_pk_mul_f32 v[176:177], v[176:177], s[0:1] op_sel_hi:[1,0]
	v_pk_mul_f32 v[174:175], v[174:175], s[0:1] op_sel_hi:[1,0]
	v_pk_fma_f32 v[24:25], v[24:25], v[132:133], v[176:177]
	v_pk_fma_f32 v[22:23], v[22:23], v[130:131], v[174:175]
	s_waitcnt vmcnt(3)
	v_pk_mul_f32 v[180:181], v[180:181], s[0:1] op_sel_hi:[1,0]
	v_pk_mul_f32 v[178:179], v[178:179], s[0:1] op_sel_hi:[1,0]
	v_pk_fma_f32 v[104:105], v[104:105], v[136:137], v[180:181]
	v_pk_fma_f32 v[102:103], v[102:103], v[134:135], v[178:179]
	s_waitcnt vmcnt(2)
	v_pk_mul_f32 v[184:185], v[184:185], s[0:1] op_sel_hi:[1,0]
	v_pk_mul_f32 v[182:183], v[182:183], s[0:1] op_sel_hi:[1,0]
	v_pk_fma_f32 v[92:93], v[92:93], v[144:145], v[184:185]
	v_pk_fma_f32 v[90:91], v[90:91], v[142:143], v[182:183]
	s_waitcnt vmcnt(1)
	v_pk_mul_f32 v[228:229], v[228:229], s[0:1] op_sel_hi:[1,0]
	v_pk_mul_f32 v[226:227], v[226:227], s[0:1] op_sel_hi:[1,0]
	v_pk_fma_f32 v[60:61], v[60:61], v[140:141], v[228:229]
	v_pk_fma_f32 v[58:59], v[58:59], v[138:139], v[226:227]
	s_waitcnt vmcnt(0)
	v_pk_mul_f32 v[232:233], v[232:233], s[0:1] op_sel_hi:[1,0]
	v_pk_mul_f32 v[230:231], v[230:231], s[0:1] op_sel_hi:[1,0]
	v_pk_fma_f32 v[28:29], v[28:29], v[132:133], v[232:233]
	v_pk_fma_f32 v[26:27], v[26:27], v[130:131], v[230:231]
	v_add_u32_e32 v160, 0xb0, v160
	v_ashrrev_i32_e32 v161, 31, v160
	v_lshlrev_b64 v[160:161], 12, v[160:161]
	v_lshl_add_u64 v[160:161], s[44:45], 0, v[160:161]
	v_lshl_add_u64 v[160:161], v[160:161], 0, v[164:165]
	v_mov_b32_e32 v170, v66
	global_load_dwordx4 v[176:179], v[160:161], off
	global_load_dwordx4 v[180:183], v[160:161], off offset:64
	global_load_dwordx4 v[200:203], v[160:161], off offset:512
	global_load_dwordx4 v[204:207], v[160:161], off offset:576
	v_mov_b32_e32 v171, v69
	v_add_f32_e32 v173, v34, v35
	v_add_f32_e32 v175, v36, v37
	v_mov_b32_e32 v172, v2
	v_mov_b32_e32 v174, v3
	v_pk_add_f32 v[170:171], v[212:213], v[170:171]
	v_pk_add_f32 v[172:173], v[172:173], v[174:175]
	v_add_f32_e32 v174, v208, v209
	v_pk_add_f32 v[170:171], v[170:171], v[170:171] op_sel_hi:[0,1]
	v_mov_b32_e32 v184, v5
	v_add_f32_e32 v185, 0, v174
	v_mov_b32_e32 v170, v4
	v_pk_add_f32 v[170:171], v[170:171], v[184:185]
	s_waitcnt vmcnt(3)
	v_pk_mul_f32 v[178:179], v[178:179], s[0:1] op_sel_hi:[1,0]
	v_pk_add_f32 v[170:171], v[172:173], v[170:171]
	v_pk_mul_f32 v[176:177], v[176:177], s[0:1] op_sel_hi:[1,0]
	v_add_f32_e32 v170, v170, v171
	ds_bpermute_b32 v172, v169, v170
	v_xor_b32_e32 v171, 32, v220
	v_cmp_lt_i32_e32 vcc, v171, v188
	s_waitcnt vmcnt(2)
	v_pk_mul_f32 v[182:183], v[182:183], s[0:1] op_sel_hi:[1,0]
	v_pk_mul_f32 v[180:181], v[180:181], s[0:1] op_sel_hi:[1,0]
	v_cndmask_b32_e32 v171, v220, v171, vcc
	v_lshlrev_b32_e32 v171, 2, v171
	s_waitcnt lgkmcnt(0)
	v_add_f32_e32 v170, v170, v172
	ds_bpermute_b32 v172, v171, v170
	s_waitcnt vmcnt(1)
	v_pk_mul_f32 v[200:201], v[200:201], s[0:1] op_sel_hi:[1,0]
	s_waitcnt vmcnt(0)
	v_pk_mul_f32 v[204:205], v[204:205], s[0:1] op_sel_hi:[1,0]
	v_pk_fma_f32 v[100:101], v[100:101], v[136:137], v[178:179]
	v_pk_fma_f32 v[98:99], v[98:99], v[134:135], v[176:177]
	s_waitcnt lgkmcnt(0)
	v_add_f32_e32 v172, v170, v172
	v_fmamk_f32 v173, v172, 0xbc800000, v129
	v_fmamk_f32 v175, v172, 0xbc800000, v127
	v_fmamk_f32 v185, v172, 0xbc800000, v69
	v_fmamk_f32 v208, v172, 0xbc800000, v67
	v_fmamk_f32 v170, v172, 0xbc800000, v128
	v_fmamk_f32 v174, v172, 0xbc800000, v126
	v_fmamk_f32 v184, v172, 0xbc800000, v68
	v_fmamk_f32 v188, v172, 0xbc800000, v66
	v_fmamk_f32 v210, v172, 0xbc800000, v37
	v_fmamk_f32 v212, v172, 0xbc800000, v35
	v_mul_f32_e32 v175, v175, v175
	v_mul_f32_e32 v173, v173, v173
	v_mul_f32_e32 v208, v208, v208
	v_mul_f32_e32 v185, v185, v185
	v_fmamk_f32 v209, v172, 0xbc800000, v36
	v_fmamk_f32 v211, v172, 0xbc800000, v34
	v_fmamk_f32 v214, v172, 0xbc800000, v5
	v_fmamk_f32 v216, v172, 0xbc800000, v3
	v_mul_f32_e32 v212, v212, v212
	v_mul_f32_e32 v210, v210, v210
	v_fmac_f32_e32 v175, v174, v174
	v_fmac_f32_e32 v173, v170, v170
	v_fmac_f32_e32 v208, v188, v188
	v_fmac_f32_e32 v185, v184, v184
	v_fmamk_f32 v213, v172, 0xbc800000, v4
	v_fmamk_f32 v215, v172, 0xbc800000, v2
	v_mul_f32_e32 v216, v216, v216
	v_mul_f32_e32 v214, v214, v214
	v_fmac_f32_e32 v212, v211, v211
	v_fmac_f32_e32 v210, v209, v209
	v_add_f32_e32 v170, v175, v173
	v_add_f32_e32 v173, v208, v185
	v_fmac_f32_e32 v216, v215, v215
	v_fmac_f32_e32 v214, v213, v213
	v_add_f32_e32 v174, v212, v210
	v_add_f32_e32 v170, v170, v173
	v_add_f32_e32 v175, v216, v214
	v_add_f32_e32 v170, v174, v170
	v_add_f32_e32 v173, v175, v170
	ds_bpermute_b32 v174, v169, v173
	v_pk_mul_f32 v[184:185], v[202:203], s[0:1] op_sel_hi:[1,0]
	v_pk_mul_f32 v[202:203], v[206:207], s[0:1] op_sel_hi:[1,0]
	v_pk_fma_f32 v[96:97], v[96:97], v[144:145], v[182:183]
	v_pk_fma_f32 v[94:95], v[94:95], v[142:143], v[180:181]
	s_waitcnt lgkmcnt(0)
	v_add_f32_e32 v173, v173, v174
	ds_bpermute_b32 v174, v171, v173
	v_pk_fma_f32 v[64:65], v[64:65], v[140:141], v[184:185]
	v_pk_fma_f32 v[62:63], v[62:63], v[138:139], v[200:201]
	v_pk_fma_f32 v[32:33], v[32:33], v[132:133], v[202:203]
	v_pk_fma_f32 v[30:31], v[30:31], v[130:131], v[204:205]
	v_and_b32_e32 v170, 63, v167
	s_lshl_b32 s0, s18, 3
	v_cmp_gt_u32_e32 vcc, 16, v170
	s_add_i32 s8, s0, 0
	s_and_saveexec_b64 s[0:1], vcc
	s_cbranch_execz .LBB0_3246
	s_lshl_b32 s9, s17, 11
	s_add_i32 s9, s8, s9
	v_mul_f32_e32 v130, 0x3c800000, v172
	v_lshl_add_u32 v132, v168, 5, s9
	s_waitcnt lgkmcnt(0)
	v_add_f32_e32 v131, v173, v174
	ds_write_b64 v132, v[130:131]
